# adaLN RMSNorm block prologues (norm1 both variants, norm2): weight/scale/shift/row-0 loads issued as one batch instead of 9 dependent round trips; same addresses and arithmetic
# baseline (speedup 1.0000x reference)
; template <bool FINAL>
; __device__ __forceinline__ void phase_norm_b(const bf16_t* xb, const float* w, const float* sc, const float* sh, bf16_t* H, float* outf, int lane, int gw, int NGW) {
;     for (int blk = gw; blk < M_TOK / 8; blk += NGW) {
;         const int m0 = blk * 8, b = m0 >> 12;
;         f32x4 A0[4], A1[4], B0[4], B1[4];
; #pragma unroll
;         for (int j = 0; j < 4; ++j) { const int col = 8 * (lane + 64 * j); A0[j] = *(const f32x4*)(w + col); A1[j] = *(const f32x4*)(w + col + 4);
;             if (!FINAL) { const float* scp = sc + (size_t)b * 12288 + col; const float* shp = sh + (size_t)b * 12288 + col;
;                 A0[j] = A0[j] * (1.0f + *(const f32x4*)scp); A1[j] = A1[j] * (1.0f + *(const f32x4*)(scp + 4)); B0[j] = *(const f32x4*)shp; B1[j] = *(const f32x4*)(shp + 4); } }
;         u32x4 nx[4];
;         { const u32x4* xr = (const u32x4*)(xb + (size_t)m0 * 2048) + lane;
; #pragma unroll
;             for (int j = 0; j < 4; ++j) nx[j] = xr[64 * j]; }
.LBB0_119:
	s_ashr_i32 s4, s22, 9
	s_mul_i32 s6, s4, 0xc000
	s_mul_hi_i32 s7, s4, 0xc000
	s_add_u32 s4, s18, s6
	s_addc_u32 s5, s19, s7
	s_add_u32 s6, s2, s6
	s_addc_u32 s7, s16, s7
	global_load_dwordx4 v[36:39], v[68:69], off
	global_load_dwordx4 v[40:43], v[68:69], off offset:16
	global_load_dwordx4 v[44:47], v[70:71], off
	global_load_dwordx4 v[48:51], v[70:71], off offset:16
	global_load_dwordx4 v[116:119], v[72:73], off
	global_load_dwordx4 v[120:123], v[72:73], off offset:16
	global_load_dwordx4 v[124:127], v[74:75], off
	global_load_dwordx4 v[128:131], v[74:75], off offset:16
	global_load_dwordx4 v[82:85], v2, s[4:5]
	global_load_dwordx4 v[86:89], v2, s[4:5] offset:16
	global_load_dwordx4 v[90:93], v2, s[4:5] offset:2048
	global_load_dwordx4 v[94:97], v2, s[4:5] offset:2064
	global_load_dwordx4 v[98:101], v78, s[4:5]
	global_load_dwordx4 v[102:105], v78, s[4:5] offset:16
	global_load_dwordx4 v[106:109], v80, s[4:5]
	global_load_dwordx4 v[110:113], v80, s[4:5] offset:16
	global_load_dwordx4 v[4:7], v2, s[6:7]
	global_load_dwordx4 v[8:11], v2, s[6:7] offset:16
	global_load_dwordx4 v[12:15], v2, s[6:7] offset:2048
	global_load_dwordx4 v[16:19], v2, s[6:7] offset:2064
	global_load_dwordx4 v[20:23], v78, s[6:7]
	global_load_dwordx4 v[24:27], v78, s[6:7] offset:16
	global_load_dwordx4 v[28:31], v80, s[6:7]
	global_load_dwordx4 v[32:35], v80, s[6:7] offset:16
	s_lshl_b32 s4, s22, 3
	s_ashr_i32 s5, s4, 31
	s_lshl_b64 s[4:5], s[4:5], 12
	s_mov_b32 s6, 0
	v_lshl_add_u64 v[132:133], v[0:1], 0, s[4:5]
	global_load_dwordx4 v[64:67], v[132:133], off
	global_load_dwordx4 v[60:63], v[132:133], off offset:1024
	global_load_dwordx4 v[56:59], v[132:133], off offset:2048
	global_load_dwordx4 v[52:55], v[132:133], off offset:3072
	s_waitcnt vmcnt(12)
	v_pk_add_f32 v[82:83], v[82:83], 1.0 op_sel_hi:[1,0]
	v_pk_add_f32 v[84:85], v[84:85], 1.0 op_sel_hi:[1,0]
	v_pk_mul_f32 v[36:37], v[36:37], v[82:83]
	v_pk_mul_f32 v[82:83], v[38:39], v[84:85]
	v_mov_b64_e32 v[84:85], v[36:37]
	v_pk_add_f32 v[86:87], v[86:87], 1.0 op_sel_hi:[1,0]
	v_pk_add_f32 v[88:89], v[88:89], 1.0 op_sel_hi:[1,0]
	v_pk_mul_f32 v[40:41], v[40:41], v[86:87]
	v_pk_mul_f32 v[86:87], v[42:43], v[88:89]
	v_mov_b64_e32 v[88:89], v[40:41]
	v_pk_add_f32 v[90:91], v[90:91], 1.0 op_sel_hi:[1,0]
	v_pk_add_f32 v[92:93], v[92:93], 1.0 op_sel_hi:[1,0]
	v_pk_mul_f32 v[44:45], v[44:45], v[90:91]
	v_pk_mul_f32 v[90:91], v[46:47], v[92:93]
	v_mov_b64_e32 v[92:93], v[44:45]
	v_pk_add_f32 v[94:95], v[94:95], 1.0 op_sel_hi:[1,0]
	v_pk_add_f32 v[96:97], v[96:97], 1.0 op_sel_hi:[1,0]
	v_pk_mul_f32 v[48:49], v[48:49], v[94:95]
	v_pk_mul_f32 v[94:95], v[50:51], v[96:97]
	v_mov_b64_e32 v[96:97], v[48:49]
	v_pk_add_f32 v[98:99], v[98:99], 1.0 op_sel_hi:[1,0]
	v_pk_add_f32 v[100:101], v[100:101], 1.0 op_sel_hi:[1,0]
	v_pk_mul_f32 v[116:117], v[116:117], v[98:99]
	v_pk_mul_f32 v[98:99], v[118:119], v[100:101]
	v_mov_b64_e32 v[100:101], v[116:117]
	v_pk_add_f32 v[102:103], v[102:103], 1.0 op_sel_hi:[1,0]
	v_pk_add_f32 v[104:105], v[104:105], 1.0 op_sel_hi:[1,0]
	v_pk_mul_f32 v[120:121], v[120:121], v[102:103]
	v_pk_mul_f32 v[102:103], v[122:123], v[104:105]
	v_mov_b64_e32 v[104:105], v[120:121]
	v_pk_add_f32 v[106:107], v[106:107], 1.0 op_sel_hi:[1,0]
	v_pk_add_f32 v[108:109], v[108:109], 1.0 op_sel_hi:[1,0]
	v_pk_mul_f32 v[124:125], v[124:125], v[106:107]
	v_pk_mul_f32 v[106:107], v[126:127], v[108:109]
	v_mov_b64_e32 v[108:109], v[124:125]
	v_pk_add_f32 v[110:111], v[110:111], 1.0 op_sel_hi:[1,0]
	v_pk_add_f32 v[112:113], v[112:113], 1.0 op_sel_hi:[1,0]
	v_pk_mul_f32 v[128:129], v[128:129], v[110:111]
	v_pk_mul_f32 v[110:111], v[130:131], v[112:113]
	v_mov_b64_e32 v[112:113], v[128:129]
	s_waitcnt vmcnt(0)
	v_mov_b64_e32 v[48:49], v[64:65]
	v_mov_b64_e32 v[44:45], v[60:61]
	v_mov_b64_e32 v[40:41], v[56:57]
	v_mov_b64_e32 v[36:37], v[52:53]
	v_mov_b64_e32 v[38:39], v[54:55]
	v_mov_b64_e32 v[42:43], v[58:59]
	v_mov_b64_e32 v[46:47], v[62:63]
	v_mov_b64_e32 v[50:51], v[66:67]
	s_branch .LBB0_121

; template <bool FINAL>
; __device__ __forceinline__ void phase_norm(const float* x, const float* w, const float* sc, const float* sh, bf16_t* H, float* outf, int lane, int gw, int NGW) {
;     for (int blk = gw; blk < M_TOK / 8; blk += NGW) {
;         const int m0 = blk * 8, b = m0 >> 12;
;         f32x4 A[8], B[8];
; #pragma unroll
;         for (int j = 0; j < 8; ++j) { const int col = 4 * (lane + 64 * j); A[j] = *(const f32x4*)(w + col);
;             if (!FINAL) { const f32x4 scv = *(const f32x4*)(sc + (size_t)b * 12288 + col); A[j] = A[j] * (1.0f + scv); B[j] = *(const f32x4*)(sh + (size_t)b * 12288 + col); } }
;         f32x4 v[8], nx[8];
;         { const f32x4* xr = (const f32x4*)(x + (size_t)m0 * 2048) + lane;
; #pragma unroll
;             for (int j = 0; j < 8; ++j) nx[j] = xr[64 * j]; }
.LBB0_128:
	s_ashr_i32 s0, s17, 9
	s_mul_hi_i32 s1, s0, 0xc000
	s_mul_i32 s0, s0, 0xc000
	s_add_u32 s4, s18, s0
	s_addc_u32 s5, s19, s1
	s_add_u32 s0, s2, s0
	s_addc_u32 s1, s16, s1
	v_mov_b32_e32 v113, v3
	v_mov_b32_e32 v115, v3
	v_mov_b32_e32 v117, v3
	v_mov_b32_e32 v119, v3
	global_load_dwordx4 v[68:71], v[100:101], off
	global_load_dwordx4 v[72:75], v[100:101], off offset:1024
	global_load_dwordx4 v[76:79], v[100:101], off offset:2048
	global_load_dwordx4 v[80:83], v[100:101], off offset:3072
	global_load_dwordx4 v[84:87], v[102:103], off
	global_load_dwordx4 v[88:91], v[104:105], off
	global_load_dwordx4 v[92:95], v[106:107], off
	global_load_dwordx4 v[96:99], v[108:109], off
	global_load_dwordx4 v[120:123], v2, s[4:5]
	global_load_dwordx4 v[124:127], v2, s[4:5] offset:1024
	global_load_dwordx4 v[128:131], v2, s[4:5] offset:2048
	global_load_dwordx4 v[132:135], v2, s[4:5] offset:3072
	global_load_dwordx4 v[136:139], v112, s[4:5]
	global_load_dwordx4 v[140:143], v114, s[4:5]
	global_load_dwordx4 v[144:147], v116, s[4:5]
	global_load_dwordx4 v[148:151], v118, s[4:5]
	global_load_dwordx4 v[4:7], v2, s[0:1]
	global_load_dwordx4 v[8:11], v2, s[0:1] offset:1024
	global_load_dwordx4 v[12:15], v2, s[0:1] offset:2048
	global_load_dwordx4 v[16:19], v2, s[0:1] offset:3072
	global_load_dwordx4 v[20:23], v112, s[0:1]
	global_load_dwordx4 v[24:27], v114, s[0:1]
	global_load_dwordx4 v[28:31], v116, s[0:1]
	global_load_dwordx4 v[32:35], v118, s[0:1]
	s_mov_b32 s4, 0
	s_lshl_b32 s0, s17, 3
	s_ashr_i32 s1, s0, 31
	s_lshl_b64 s[0:1], s[0:1], 13
	v_lshl_add_u64 v[152:153], v[0:1], 0, s[0:1]
	s_add_u32 s0, s0, 0x1000
	s_addc_u32 s1, s1, 0
	v_lshl_add_u64 v[36:37], v[0:1], 0, s[0:1]
	global_load_dwordx4 v[64:67], v[152:153], off
	global_load_dwordx4 v[60:63], v[152:153], off offset:1024
	global_load_dwordx4 v[52:55], v[152:153], off offset:2048
	global_load_dwordx4 v[44:47], v[152:153], off offset:3072
	global_load_dwordx4 v[56:59], v[36:37], off
	global_load_dwordx4 v[48:51], v[36:37], off offset:1024
	global_load_dwordx4 v[40:43], v[36:37], off offset:2048
	s_nop 0
	global_load_dwordx4 v[36:39], v[36:37], off offset:3072
	s_waitcnt vmcnt(16)
	v_pk_add_f32 v[120:121], v[120:121], 1.0 op_sel_hi:[1,0]
	v_pk_add_f32 v[122:123], v[122:123], 1.0 op_sel_hi:[1,0]
	v_pk_mul_f32 v[68:69], v[68:69], v[120:121]
	v_pk_mul_f32 v[120:121], v[70:71], v[122:123]
	v_mov_b64_e32 v[122:123], v[68:69]
	v_pk_add_f32 v[124:125], v[124:125], 1.0 op_sel_hi:[1,0]
	v_pk_add_f32 v[126:127], v[126:127], 1.0 op_sel_hi:[1,0]
	v_pk_mul_f32 v[72:73], v[72:73], v[124:125]
	v_pk_mul_f32 v[124:125], v[74:75], v[126:127]
	v_mov_b64_e32 v[126:127], v[72:73]
	v_pk_add_f32 v[128:129], v[128:129], 1.0 op_sel_hi:[1,0]
	v_pk_add_f32 v[130:131], v[130:131], 1.0 op_sel_hi:[1,0]
	v_pk_mul_f32 v[76:77], v[76:77], v[128:129]
	v_pk_mul_f32 v[128:129], v[78:79], v[130:131]
	v_mov_b64_e32 v[130:131], v[76:77]
	v_pk_add_f32 v[132:133], v[132:133], 1.0 op_sel_hi:[1,0]
	v_pk_add_f32 v[134:135], v[134:135], 1.0 op_sel_hi:[1,0]
	v_pk_mul_f32 v[80:81], v[80:81], v[132:133]
	v_pk_mul_f32 v[132:133], v[82:83], v[134:135]
	v_mov_b64_e32 v[134:135], v[80:81]
	v_pk_add_f32 v[136:137], v[136:137], 1.0 op_sel_hi:[1,0]
	v_pk_add_f32 v[138:139], v[138:139], 1.0 op_sel_hi:[1,0]
	v_pk_mul_f32 v[84:85], v[84:85], v[136:137]
	v_pk_mul_f32 v[136:137], v[86:87], v[138:139]
	v_mov_b64_e32 v[138:139], v[84:85]
	v_pk_add_f32 v[140:141], v[140:141], 1.0 op_sel_hi:[1,0]
	v_pk_add_f32 v[142:143], v[142:143], 1.0 op_sel_hi:[1,0]
	v_pk_mul_f32 v[88:89], v[88:89], v[140:141]
	v_pk_mul_f32 v[140:141], v[90:91], v[142:143]
	v_mov_b64_e32 v[142:143], v[88:89]
	v_pk_add_f32 v[144:145], v[144:145], 1.0 op_sel_hi:[1,0]
	v_pk_add_f32 v[146:147], v[146:147], 1.0 op_sel_hi:[1,0]
	v_pk_mul_f32 v[92:93], v[92:93], v[144:145]
	v_pk_mul_f32 v[144:145], v[94:95], v[146:147]
	v_mov_b64_e32 v[146:147], v[92:93]
	v_pk_add_f32 v[148:149], v[148:149], 1.0 op_sel_hi:[1,0]
	v_pk_add_f32 v[150:151], v[150:151], 1.0 op_sel_hi:[1,0]
	v_pk_mul_f32 v[96:97], v[96:97], v[148:149]
	v_pk_mul_f32 v[148:149], v[98:99], v[150:151]
	v_mov_b64_e32 v[150:151], v[96:97]
	s_waitcnt vmcnt(0)
	v_mov_b64_e32 v[82:83], v[66:67]
	v_mov_b64_e32 v[70:71], v[46:47]
	v_mov_b64_e32 v[74:75], v[54:55]
	v_mov_b64_e32 v[78:79], v[62:63]
	v_mov_b64_e32 v[68:69], v[44:45]
	v_mov_b64_e32 v[72:73], v[52:53]
	v_mov_b64_e32 v[76:77], v[60:61]
	v_mov_b64_e32 v[80:81], v[64:65]
	v_mov_b64_e32 v[98:99], v[58:59]
	v_mov_b64_e32 v[94:95], v[50:51]
	v_mov_b64_e32 v[90:91], v[42:43]
	v_mov_b64_e32 v[86:87], v[38:39]
	v_mov_b64_e32 v[84:85], v[36:37]
	v_mov_b64_e32 v[88:89], v[40:41]
	v_mov_b64_e32 v[92:93], v[48:49]
	v_mov_b64_e32 v[96:97], v[56:57]
	s_branch .LBB0_130

; template <bool FINAL>
; __device__ __forceinline__ void phase_norm_b(const bf16_t* xb, const float* w, const float* sc, const float* sh, bf16_t* H, float* outf, int lane, int gw, int NGW) {
;     for (int blk = gw; blk < M_TOK / 8; blk += NGW) {
;         const int m0 = blk * 8, b = m0 >> 12;
;         f32x4 A0[4], A1[4], B0[4], B1[4];
; #pragma unroll
;         for (int j = 0; j < 4; ++j) { const int col = 8 * (lane + 64 * j); A0[j] = *(const f32x4*)(w + col); A1[j] = *(const f32x4*)(w + col + 4);
;             if (!FINAL) { const float* scp = sc + (size_t)b * 12288 + col; const float* shp = sh + (size_t)b * 12288 + col;
;                 A0[j] = A0[j] * (1.0f + *(const f32x4*)scp); A1[j] = A1[j] * (1.0f + *(const f32x4*)(scp + 4)); B0[j] = *(const f32x4*)shp; B1[j] = *(const f32x4*)(shp + 4); } }
;         u32x4 nx[4];
;         { const u32x4* xr = (const u32x4*)(xb + (size_t)m0 * 2048) + lane;
; #pragma unroll
;             for (int j = 0; j < 4; ++j) nx[j] = xr[64 * j]; }
.LBB0_726:
	s_ashr_i32 s0, s2, 9
	s_mul_i32 s4, s0, 0xc000
	s_mul_hi_i32 s5, s0, 0xc000
	s_add_u32 s0, s6, s4
	s_addc_u32 s1, s7, s5
	s_add_u32 s4, s16, s4
	s_addc_u32 s5, s17, s5
	v_mov_b32_e32 v77, v3
	v_mov_b32_e32 v79, v3
	global_load_dwordx4 v[36:39], v[68:69], off
	global_load_dwordx4 v[40:43], v[68:69], off offset:16
	global_load_dwordx4 v[44:47], v[68:69], off offset:2048
	global_load_dwordx4 v[48:51], v[68:69], off offset:2064
	global_load_dwordx4 v[112:115], v[70:71], off
	global_load_dwordx4 v[116:119], v[70:71], off offset:16
	global_load_dwordx4 v[120:123], v[72:73], off
	global_load_dwordx4 v[124:127], v[72:73], off offset:16
	global_load_dwordx4 v[80:83], v2, s[0:1]
	global_load_dwordx4 v[84:87], v2, s[0:1] offset:16
	global_load_dwordx4 v[88:91], v2, s[0:1] offset:2048
	global_load_dwordx4 v[92:95], v2, s[0:1] offset:2064
	global_load_dwordx4 v[96:99], v76, s[0:1]
	global_load_dwordx4 v[100:103], v76, s[0:1] offset:16
	global_load_dwordx4 v[104:107], v78, s[0:1]
	global_load_dwordx4 v[108:111], v78, s[0:1] offset:16
	global_load_dwordx4 v[4:7], v2, s[4:5]
	global_load_dwordx4 v[8:11], v2, s[4:5] offset:16
	global_load_dwordx4 v[12:15], v2, s[4:5] offset:2048
	global_load_dwordx4 v[16:19], v2, s[4:5] offset:2064
	global_load_dwordx4 v[20:23], v76, s[4:5]
	global_load_dwordx4 v[24:27], v76, s[4:5] offset:16
	global_load_dwordx4 v[28:31], v78, s[4:5]
	global_load_dwordx4 v[32:35], v78, s[4:5] offset:16
	s_lshl_b32 s0, s2, 3
	s_ashr_i32 s1, s0, 31
	s_lshl_b64 s[0:1], s[0:1], 12
	s_mov_b32 s4, 0
	v_lshl_add_u64 v[128:129], v[0:1], 0, s[0:1]
	global_load_dwordx4 v[64:67], v[128:129], off
	global_load_dwordx4 v[60:63], v[128:129], off offset:1024
	global_load_dwordx4 v[56:59], v[128:129], off offset:2048
	global_load_dwordx4 v[52:55], v[128:129], off offset:3072
	s_waitcnt vmcnt(12)
	v_pk_add_f32 v[80:81], v[80:81], 1.0 op_sel_hi:[1,0]
	v_pk_add_f32 v[82:83], v[82:83], 1.0 op_sel_hi:[1,0]
	v_pk_mul_f32 v[36:37], v[36:37], v[80:81]
	v_pk_mul_f32 v[80:81], v[38:39], v[82:83]
	v_mov_b64_e32 v[82:83], v[36:37]
	v_pk_add_f32 v[84:85], v[84:85], 1.0 op_sel_hi:[1,0]
	v_pk_add_f32 v[86:87], v[86:87], 1.0 op_sel_hi:[1,0]
	v_pk_mul_f32 v[40:41], v[40:41], v[84:85]
	v_pk_mul_f32 v[84:85], v[42:43], v[86:87]
	v_mov_b64_e32 v[86:87], v[40:41]
	v_pk_add_f32 v[88:89], v[88:89], 1.0 op_sel_hi:[1,0]
	v_pk_add_f32 v[90:91], v[90:91], 1.0 op_sel_hi:[1,0]
	v_pk_mul_f32 v[44:45], v[44:45], v[88:89]
	v_pk_mul_f32 v[88:89], v[46:47], v[90:91]
	v_mov_b64_e32 v[90:91], v[44:45]
	v_pk_add_f32 v[92:93], v[92:93], 1.0 op_sel_hi:[1,0]
	v_pk_add_f32 v[94:95], v[94:95], 1.0 op_sel_hi:[1,0]
	v_pk_mul_f32 v[48:49], v[48:49], v[92:93]
	v_pk_mul_f32 v[92:93], v[50:51], v[94:95]
	v_mov_b64_e32 v[94:95], v[48:49]
	v_pk_add_f32 v[96:97], v[96:97], 1.0 op_sel_hi:[1,0]
	v_pk_add_f32 v[98:99], v[98:99], 1.0 op_sel_hi:[1,0]
	v_pk_mul_f32 v[112:113], v[112:113], v[96:97]
	v_pk_mul_f32 v[96:97], v[114:115], v[98:99]
	v_mov_b64_e32 v[98:99], v[112:113]
	v_pk_add_f32 v[100:101], v[100:101], 1.0 op_sel_hi:[1,0]
	v_pk_add_f32 v[102:103], v[102:103], 1.0 op_sel_hi:[1,0]
	v_pk_mul_f32 v[116:117], v[116:117], v[100:101]
	v_pk_mul_f32 v[100:101], v[118:119], v[102:103]
	v_mov_b64_e32 v[102:103], v[116:117]
	v_pk_add_f32 v[104:105], v[104:105], 1.0 op_sel_hi:[1,0]
	v_pk_add_f32 v[106:107], v[106:107], 1.0 op_sel_hi:[1,0]
	v_pk_mul_f32 v[120:121], v[120:121], v[104:105]
	v_pk_mul_f32 v[104:105], v[122:123], v[106:107]
	v_mov_b64_e32 v[106:107], v[120:121]
	v_pk_add_f32 v[108:109], v[108:109], 1.0 op_sel_hi:[1,0]
	v_pk_add_f32 v[110:111], v[110:111], 1.0 op_sel_hi:[1,0]
	v_pk_mul_f32 v[124:125], v[124:125], v[108:109]
	v_pk_mul_f32 v[108:109], v[126:127], v[110:111]
	v_mov_b64_e32 v[110:111], v[124:125]
	s_waitcnt vmcnt(0)
	v_mov_b64_e32 v[48:49], v[64:65]
	v_mov_b64_e32 v[44:45], v[60:61]
	v_mov_b64_e32 v[40:41], v[56:57]
	v_mov_b64_e32 v[36:37], v[52:53]
	v_mov_b64_e32 v[38:39], v[54:55]
	v_mov_b64_e32 v[42:43], v[58:59]
	v_mov_b64_e32 v[46:47], v[62:63]
	v_mov_b64_e32 v[50:51], v[66:67]
	s_branch .LBB0_728
